# DSA sparse PV operand built with ds_read_b64_tr_b16 transpose loads (16 reads instead of 64 u16 reads + packs per 32-key chunk) and kSpStart work dealing re-balanced for the faster sparse queries
# speedup vs baseline: 1.0226x; 1.0203x over previous
; #define MFMA16(a, b, c) __builtin_amdgcn_mfma_f32_16x16x32_bf16((a), (b), (c), 0, 0, 0)
; DI void dsa_sparse_phase(unsigned char* lds, KParamPtr P, int wv) {
;     ...
;     for (int ch = 0; ch < 8; ++ch) {
; #pragma unroll
;       for (int i = 0; i < 8; ++i) *(u32x4*)(gbuf + (grow + 4 * i) * 136 + gc16 * 8) = gr[i];
;       asm volatile("" ::: "memory");
;       {
;         const int cn = ch < 7 ? ch + 1 : ch;
; #pragma unroll
;         for (int i = 0; i < 8; ++i) {
;           int id = idL[cn * 32 + grow + 4 * i]; id = id > SEQ - 1 ? SEQ - 1 : id;
;           gr[i] = *(const u32x4*)(ckv + cb + (unsigned)id * 128u);
;         }
;       }
;       f32x4 a[2];
; #pragma unroll
;       for (int tl = 0; tl < 2; ++tl) {
;         f32x4 acc = (f32x4){0.f, 0.f, 0.f, 0.f};
; #pragma unroll
;         for (int st = 0; st < 4; ++st) acc = MFMA16(*(const bf16x8*)(gbuf + (rk + 4 * tl) * 136 + st * 32 + q4 * 8), qf[st], acc);
;         a[tl] = acc;
;       }
;       float mloc = NEGB;
; #pragma unroll
;       for (int tl = 0; tl < 2; ++tl)
; #pragma unroll
;         for (int j = 0; j < 4; ++j) {
;           const int id = idL[ch * 32 + 8 * q4 + 4 * tl + j];
;           const int dist = tq - id; const int dd = dist < 0 ? 0 : (dist > 127 ? 127 : dist);
;           const float tb = tabc[dd];
;           float z = fmaf(a[tl][j], C1, tb); z = dist < 0 ? NEGB : z;
;           a[tl][j] = z; mloc = fmaxf(mloc, z);
;         }
.LBB0_1186:
	s_cmpk_lg_i32 s22, 0x100
	s_waitcnt vmcnt(0) lgkmcnt(0)
	ds_write_b128 v112, v[18:21] offset:12288
	ds_write_b128 v112, v[22:25] offset:13376
	ds_write_b128 v112, v[26:29] offset:14464
	ds_write_b128 v112, v[30:33] offset:15552
	ds_write_b128 v112, v[34:37] offset:16640
	ds_write_b128 v112, v[38:41] offset:17728
	ds_write_b128 v112, v[42:45] offset:18816
	ds_write_b128 v112, v[46:49] offset:19904
	s_cselect_b32 s2, s22, 0xe0
	v_lshl_add_u32 v0, s2, 1, v109
	ds_read_u16 v18, v0 offset:20992
	ds_read_u16 v22, v0 offset:21000
	ds_read_u16 v26, v0 offset:21008
	ds_read_u16 v30, v0 offset:21016
	ds_read_u16 v34, v0 offset:21024
	ds_read_u16 v38, v0 offset:21032
	ds_read_u16 v42, v0 offset:21040
	ds_read_u16 v46, v0 offset:21048
	ds_read_b128 v[82:85], v113 offset:12288
	v_mov_b32_e32 v116, v118
	ds_read_b128 v[118:121], v113 offset:12352
	s_waitcnt lgkmcnt(9)
	v_min_u16_e32 v0, 0x1fff, v18
	v_lshlrev_b32_e32 v0, 8, v0
	v_lshl_add_u64 v[18:19], v[100:101], 0, v[0:1]
	s_waitcnt lgkmcnt(1)
	v_mfma_f32_16x16x32_bf16 v[82:85], v[82:85], v[6:9], 0
	ds_read_b128 v[122:125], v113 offset:13440
	v_min_u16_e32 v0, 0x1fff, v22
	v_lshlrev_b32_e32 v0, 8, v0
	s_waitcnt lgkmcnt(1)
	v_mfma_f32_16x16x32_bf16 v[82:85], v[118:121], v[2:5], v[82:85]
	ds_read_b128 v[118:121], v113 offset:12416
	v_lshl_add_u64 v[22:23], v[100:101], 0, v[0:1]
	v_min_u16_e32 v0, 0x1fff, v26
	v_lshlrev_b32_e32 v0, 8, v0
	v_lshl_add_u64 v[26:27], v[100:101], 0, v[0:1]
	s_waitcnt lgkmcnt(0)
	v_mfma_f32_16x16x32_bf16 v[82:85], v[118:121], v[14:17], v[82:85]
	ds_read_b128 v[118:121], v113 offset:12480
	v_min_u16_e32 v0, 0x1fff, v30
	v_lshlrev_b32_e32 v0, 8, v0
	v_lshl_add_u64 v[30:31], v[100:101], 0, v[0:1]
	s_waitcnt lgkmcnt(0)
	v_mfma_f32_16x16x32_bf16 v[82:85], v[118:121], v[10:13], v[82:85]
	ds_read_b128 v[118:121], v113 offset:13376
	v_min_u16_e32 v0, 0x1fff, v34
	v_lshlrev_b32_e32 v0, 8, v0
	s_waitcnt lgkmcnt(0)
	v_mfma_f32_16x16x32_bf16 v[118:121], v[118:121], v[6:9], 0
	v_lshl_add_u64 v[34:35], v[100:101], 0, v[0:1]
	v_min_u16_e32 v0, 0x1fff, v38
	v_lshlrev_b32_e32 v0, 8, v0
	v_mfma_f32_16x16x32_bf16 v[118:121], v[122:125], v[2:5], v[118:121]
	ds_read_b128 v[122:125], v113 offset:13504
	v_lshl_add_u64 v[38:39], v[100:101], 0, v[0:1]
	v_min_u16_e32 v0, 0x1fff, v42
	s_waitcnt lgkmcnt(0)
	v_mfma_f32_16x16x32_bf16 v[118:121], v[122:125], v[14:17], v[118:121]
	ds_read_b128 v[122:125], v113 offset:13568
	v_lshlrev_b32_e32 v0, 8, v0
	v_lshl_add_u64 v[42:43], v[100:101], 0, v[0:1]
	s_waitcnt lgkmcnt(0)
	v_mfma_f32_16x16x32_bf16 v[118:121], v[122:125], v[10:13], v[118:121]
	ds_read_b128 v[122:125], v115
	v_min_u16_e32 v0, 0x1fff, v46
	v_lshlrev_b32_e32 v0, 8, v0
	v_lshl_add_u64 v[46:47], v[100:101], 0, v[0:1]
	flat_load_dwordx4 v[18:21], v[18:19]
	s_waitcnt lgkmcnt(0)
	v_sub_u32_sdwa v0, v103, v125 dst_sel:DWORD dst_unused:UNUSED_PAD src0_sel:DWORD src1_sel:WORD_1
	v_sub_u32_sdwa v87, v102, v125 dst_sel:DWORD dst_unused:UNUSED_PAD src0_sel:DWORD src1_sel:WORD_0
	v_med3_i32 v88, v87, 0, v216
	v_med3_i32 v89, v0, 0, v216
	v_lshl_add_u32 v88, v88, 2, v106
	v_lshl_add_u32 v89, v89, 2, v106
	ds_read_b32 v88, v88 offset:4096
	ds_read_b32 v89, v89 offset:4096
	v_cmp_lt_i32_e32 vcc, -1, v0
	v_sub_u32_sdwa v117, v103, v124 dst_sel:DWORD dst_unused:UNUSED_PAD src0_sel:DWORD src1_sel:WORD_1
	flat_load_dwordx4 v[22:25], v[22:23]
	s_add_i32 s22, s22, 32
	s_waitcnt lgkmcnt(0)
	v_pk_fma_f32 v[88:89], v[120:121], s[44:45], v[88:89] op_sel_hi:[1,0,1]
	v_sub_u32_sdwa v120, v102, v124 dst_sel:DWORD dst_unused:UNUSED_PAD src0_sel:DWORD src1_sel:WORD_0
	v_cndmask_b32_e32 v0, v217, v89, vcc
	v_cmp_lt_i32_e32 vcc, -1, v87
	v_med3_i32 v89, v117, 0, v216
	v_lshl_add_u32 v89, v89, 2, v106
	v_cndmask_b32_e32 v87, v217, v88, vcc
	v_med3_i32 v88, v120, 0, v216
	v_lshl_add_u32 v88, v88, 2, v106
	ds_read_b32 v88, v88 offset:4096
	ds_read_b32 v89, v89 offset:4096
	v_cmp_lt_i32_e32 vcc, -1, v117
	v_sub_u32_sdwa v117, v103, v123 dst_sel:DWORD dst_unused:UNUSED_PAD src0_sel:DWORD src1_sel:WORD_1
	v_cmp_lt_i32_e64 s[8:9], -1, v117
	flat_load_dwordx4 v[26:29], v[26:27]
	s_waitcnt lgkmcnt(0)
	v_pk_fma_f32 v[88:89], v[118:119], s[44:45], v[88:89] op_sel_hi:[1,0,1]
	flat_load_dwordx4 v[30:33], v[30:31]
	v_cndmask_b32_e32 v118, v217, v89, vcc
	v_cmp_lt_i32_e32 vcc, -1, v120
	v_sub_u32_sdwa v120, v102, v123 dst_sel:DWORD dst_unused:UNUSED_PAD src0_sel:DWORD src1_sel:WORD_0
	v_med3_i32 v89, v117, 0, v216
	v_cndmask_b32_e32 v119, v217, v88, vcc
	v_med3_i32 v88, v120, 0, v216
	v_lshl_add_u32 v88, v88, 2, v106
	v_lshl_add_u32 v89, v89, 2, v106
	ds_read_b32 v88, v88 offset:4096
	ds_read_b32 v89, v89 offset:4096
	v_sub_u32_sdwa v117, v103, v122 dst_sel:DWORD dst_unused:UNUSED_PAD src0_sel:DWORD src1_sel:WORD_1
	v_cmp_lt_i32_e64 s[12:13], -1, v117
	v_cmp_lt_f32_e64 s[6:7], s62, v118
	v_cmp_lt_f32_e32 vcc, s62, v119
	s_waitcnt lgkmcnt(0)
	v_pk_fma_f32 v[84:85], v[84:85], s[44:45], v[88:89] op_sel_hi:[1,0,1]
	flat_load_dwordx4 v[34:37], v[34:35]
	v_cndmask_b32_e64 v88, v217, v85, s[8:9]
	v_cmp_lt_i32_e64 s[8:9], -1, v120
	v_sub_u32_sdwa v120, v102, v122 dst_sel:DWORD dst_unused:UNUSED_PAD src0_sel:DWORD src1_sel:WORD_0
	v_med3_i32 v85, v117, 0, v216
	v_cndmask_b32_e64 v89, v217, v84, s[8:9]
	v_med3_i32 v84, v120, 0, v216
	v_lshl_add_u32 v84, v84, 2, v106
	v_lshl_add_u32 v85, v85, 2, v106
	ds_read_b32 v84, v84 offset:4096
	ds_read_b32 v85, v85 offset:4096
	v_cmp_lt_f32_e64 s[10:11], s62, v88
	v_cmp_lt_f32_e64 s[8:9], s62, v89
	flat_load_dwordx4 v[38:41], v[38:39]
	v_add_u32_e32 v115, 64, v115
	s_waitcnt lgkmcnt(0)
; #define MFMA16(a, b, c) __builtin_amdgcn_mfma_f32_16x16x32_bf16((a), (b), (c), 0, 0, 0)
; DI unsigned pk2(float a, float b) { f32x2 v = {a, b}; bfx2 r = __builtin_convertvector(v, bfx2); return __builtin_bit_cast(unsigned, r); }
; DI float ex2(float x) { return __builtin_amdgcn_exp2f(x); }
; DI float red_max32(float x) { auto r = __builtin_amdgcn_permlane32_swap(__float_as_uint(x), __float_as_uint(x), false, false); return fmaxf(__uint_as_float(r[0]), __uint_as_float(r[1])); }
; DI float red_max16(float x) { auto r = __builtin_amdgcn_permlane16_swap(__float_as_uint(x), __float_as_uint(x), false, false); return fmaxf(__uint_as_float(r[0]), __uint_as_float(r[1])); }
; DI void dsa_sparse_phase(unsigned char* lds, KParamPtr P, int wv) {
;     ...
;       mloc = red_max16(mloc);
;       mloc = red_max32(mloc);
;       const float mn = fmaxf(m, mloc);
;       const float alpha = ex2(m - mn);
;       float ls = 0.f;
; #pragma unroll
;       for (int tl = 0; tl < 2; ++tl)
; #pragma unroll
;         for (int j = 0; j < 4; ++j) { float p = (a[tl][j] > -1e29f) ? ex2(a[tl][j] - mn) : 0.f; a[tl][j] = p; ls += p; }
;       l = l * alpha + ls; m = mn;
; #pragma unroll
;       for (int e = 0; e < 8; ++e) O[e] *= alpha;
;       u32x4 u; u.x = pk2(a[0][0], a[0][1]); u.y = pk2(a[0][2], a[0][3]); u.z = pk2(a[1][0], a[1][1]); u.w = pk2(a[1][2], a[1][3]);
;       const bf16x8 pf = __builtin_bit_cast(bf16x8, u);
; #pragma unroll
;       for (int rt = 0; rt < 8; ++rt) {
;         const bf16_t* gp = gbuf + (8 * q4) * 136 + rt * 16 + col;
;         u32x4 v;
;         v.x = (unsigned)gp[0] | ((unsigned)gp[136] << 16); v.y = (unsigned)gp[2 * 136] | ((unsigned)gp[3 * 136] << 16);
;         v.z = (unsigned)gp[4 * 136] | ((unsigned)gp[5 * 136] << 16); v.w = (unsigned)gp[6 * 136] | ((unsigned)gp[7 * 136] << 16);
;         O[rt] = MFMA16(__builtin_bit_cast(bf16x8, v), pf, O[rt]);
;       }
;       asm volatile("" ::: "memory");
	v_pk_fma_f32 v[82:83], v[82:83], s[44:45], v[84:85] op_sel_hi:[1,0,1]
	flat_load_dwordx4 v[42:45], v[42:43]
	v_cndmask_b32_e64 v83, v217, v83, s[12:13]
	v_cmp_lt_i32_e64 s[12:13], -1, v120
	v_cmp_lt_f32_e64 s[14:15], s62, v83
	flat_load_dwordx4 v[46:49], v[46:47]
	v_cndmask_b32_e64 v82, v217, v82, s[12:13]
	v_max3_f32 v84, v82, s52, v83
	v_max3_f32 v84, v84, v89, v88
	v_max3_f32 v84, v84, v119, v118
	v_max3_f32 v84, v84, v87, v0
	v_mov_b32_e32 v85, v84
	s_nop 1
	v_permlane16_swap_b32_e32 v84, v85
	v_max_f32_e32 v85, v85, v85
	v_max_f32_e32 v84, v84, v84
	v_max_f32_e32 v84, v84, v85
	v_mov_b32_e32 v85, v84
	s_nop 1
	v_permlane32_swap_b32_e32 v84, v85
	v_max3_f32 v117, v86, v84, v85
	v_cmp_lt_f32_e64 s[12:13], s62, v82
	v_sub_f32_e32 v82, v82, v117
	v_sub_f32_e32 v118, v118, v117
	v_exp_f32_e32 v82, v82
	v_sub_f32_e32 v83, v83, v117
	v_exp_f32_e32 v118, v118
	v_sub_f32_e32 v84, v86, v117
	v_exp_f32_e32 v83, v83
	v_sub_f32_e32 v86, v89, v117
	v_exp_f32_e32 v86, v86
	v_sub_f32_e32 v88, v88, v117
	v_exp_f32_e32 v88, v88
	v_sub_f32_e32 v89, v119, v117
	v_cndmask_b32_e64 v82, 0, v82, s[12:13]
	v_exp_f32_e32 v89, v89
	v_cndmask_b32_e64 v119, 0, v118, s[6:7]
	v_cmp_lt_f32_e64 s[6:7], s62, v0
	v_sub_f32_e32 v0, v0, v117
	v_cndmask_b32_e64 v83, 0, v83, s[14:15]
	v_add_f32_e32 v85, 0, v82
	v_sub_f32_e32 v118, v87, v117
	v_exp_f32_e32 v0, v0
	v_add_f32_e32 v85, v83, v85
	v_cndmask_b32_e64 v86, 0, v86, s[8:9]
	v_exp_f32_e32 v118, v118
	v_cndmask_b32_e64 v88, 0, v88, s[10:11]
	v_add_f32_e32 v85, v86, v85
	v_add_f32_e32 v85, v88, v85
	v_cndmask_b32_e32 v89, 0, v89, vcc
	v_cmp_lt_f32_e32 vcc, s62, v87
	v_cndmask_b32_e64 v87, 0, v0, s[6:7]
	v_exp_f32_e32 v0, v84
	v_add_f32_e32 v84, v89, v85
	v_cndmask_b32_e32 v120, 0, v118, vcc
	v_add_f32_e32 v84, v119, v84
	v_add_f32_e32 v84, v120, v84
	v_add_f32_e32 v118, v87, v84
	v_cvt_pk_bf16_f32 v82, v82, v83
	v_cvt_pk_bf16_f32 v83, v86, v88
	v_cvt_pk_bf16_f32 v84, v89, v119
	v_cvt_pk_bf16_f32 v85, v120, v87
	v_mbcnt_lo_u32_b32 v196, -1, 0
	v_mbcnt_hi_u32_b32 v196, -1, v196
	v_and_b32_e32 v197, 15, v196
	v_lshrrev_b32_e32 v198, 2, v197
	v_mul_u32_u24_e32 v198, 0x110, v198
	v_and_b32_e32 v196, 3, v197
	v_lshl_add_u32 v198, v196, 3, v198
	v_lshlrev_b32_e32 v197, 1, v197
	v_sub_u32_e32 v198, v198, v197
	v_add_u32_e32 v198, v110, v198
	ds_read_b64_tr_b16 v[164:165], v198 offset:12288
	ds_read_b64_tr_b16 v[166:167], v198 offset:13376
	ds_read_b64_tr_b16 v[168:169], v198 offset:12320
	ds_read_b64_tr_b16 v[170:171], v198 offset:13408
	ds_read_b64_tr_b16 v[172:173], v198 offset:12352
	ds_read_b64_tr_b16 v[174:175], v198 offset:13440
	ds_read_b64_tr_b16 v[176:177], v198 offset:12384
	ds_read_b64_tr_b16 v[178:179], v198 offset:13472
	ds_read_b64_tr_b16 v[180:181], v198 offset:12416
	ds_read_b64_tr_b16 v[182:183], v198 offset:13504
	ds_read_b64_tr_b16 v[184:185], v198 offset:12448
	ds_read_b64_tr_b16 v[186:187], v198 offset:13536
	ds_read_b64_tr_b16 v[188:189], v198 offset:12480
	ds_read_b64_tr_b16 v[190:191], v198 offset:13568
	ds_read_b64_tr_b16 v[192:193], v198 offset:12512
	ds_read_b64_tr_b16 v[194:195], v198 offset:13600
	v_pk_mul_f32 v[56:57], v[56:57], v[0:1] op_sel_hi:[1,0]
	v_pk_mul_f32 v[54:55], v[54:55], v[0:1] op_sel_hi:[1,0]
	v_pk_mul_f32 v[52:53], v[52:53], v[0:1] op_sel_hi:[1,0]
	v_pk_mul_f32 v[50:51], v[50:51], v[0:1] op_sel_hi:[1,0]
	v_pk_mul_f32 v[60:61], v[60:61], v[0:1] op_sel_hi:[1,0]
	v_pk_mul_f32 v[58:59], v[58:59], v[0:1] op_sel_hi:[1,0]
	v_pk_mul_f32 v[64:65], v[64:65], v[0:1] op_sel_hi:[1,0]
	v_pk_mul_f32 v[62:63], v[62:63], v[0:1] op_sel_hi:[1,0]
	v_pk_mul_f32 v[68:69], v[68:69], v[0:1] op_sel_hi:[1,0]
	v_pk_mul_f32 v[66:67], v[66:67], v[0:1] op_sel_hi:[1,0]
	v_pk_mul_f32 v[72:73], v[72:73], v[0:1] op_sel_hi:[1,0]
	v_pk_mul_f32 v[70:71], v[70:71], v[0:1] op_sel_hi:[1,0]
	v_pk_mul_f32 v[76:77], v[76:77], v[0:1] op_sel_hi:[1,0]
	v_pk_mul_f32 v[74:75], v[74:75], v[0:1] op_sel_hi:[1,0]
	v_pk_mul_f32 v[80:81], v[80:81], v[0:1] op_sel_hi:[1,0]
	v_pk_mul_f32 v[78:79], v[78:79], v[0:1] op_sel_hi:[1,0]
	v_fmac_f32_e32 v118, v116, v0
	s_cmpk_lg_i32 s22, 0x120
	s_waitcnt lgkmcnt(14)
	v_mfma_f32_16x16x32_bf16 v[54:57], v[164:167], v[82:85], v[54:57]
	s_waitcnt lgkmcnt(12)
	v_mfma_f32_16x16x32_bf16 v[50:53], v[168:171], v[82:85], v[50:53]
	s_waitcnt lgkmcnt(10)
	v_mfma_f32_16x16x32_bf16 v[58:61], v[172:175], v[82:85], v[58:61]
	s_waitcnt lgkmcnt(8)
	v_mfma_f32_16x16x32_bf16 v[62:65], v[176:179], v[82:85], v[62:65]
	s_waitcnt lgkmcnt(6)
	v_mfma_f32_16x16x32_bf16 v[66:69], v[180:183], v[82:85], v[66:69]
	s_waitcnt lgkmcnt(4)
	v_mfma_f32_16x16x32_bf16 v[70:73], v[184:187], v[82:85], v[70:73]
	s_waitcnt lgkmcnt(2)
	v_mfma_f32_16x16x32_bf16 v[74:77], v[188:191], v[82:85], v[74:77]
	s_waitcnt lgkmcnt(0)
	v_mfma_f32_16x16x32_bf16 v[78:81], v[192:195], v[82:85], v[78:81]
	v_mov_b32_e32 v86, v117
	s_cbranch_scc1 .LBB0_1186
; DI u32x2 pk4(float a, float b, float c, float d) { u32x2 r; r.x = pk2(a, b); r.y = pk2(c, d); return r; }
; DI float red_sum32(float x) { auto r = __builtin_amdgcn_permlane32_swap(__float_as_uint(x), __float_as_uint(x), false, false); return __uint_as_float(r[0]) + __uint_as_float(r[1]); }
; DI float red_sum16(float x) { auto r = __builtin_amdgcn_permlane16_swap(__float_as_uint(x), __float_as_uint(x), false, false); return __uint_as_float(r[0]) + __uint_as_float(r[1]); }
; DI void dsa_sparse_phase(unsigned char* lds, KParamPtr P, int wv) {
;     ...
;     l = red_sum16(l);
;     l = red_sum32(l);
;     if (col < 8) {
;       const float inv = 1.f / l;
;       bf16_t* op = qlat + (size_t)q * DM + col * 128;
; #pragma unroll
;       for (int rt = 0; rt < 8; ++rt) *(u32x2*)(op + rt * 16 + 4 * q4) = pk4(O[rt][0] * inv, O[rt][1] * inv, O[rt][2] * inv, O[rt][3] * inv);
;     }
	v_mov_b32_e32 v0, v118
	s_nop 1
	v_permlane16_swap_b32_e32 v118, v0
	v_add_f32_e32 v0, v118, v0
	v_mov_b32_e32 v2, v0
	s_nop 1
	v_permlane32_swap_b32_e32 v0, v2
	s_and_saveexec_b64 s[6:7], s[4:5]
	s_cbranch_execz .LBB0_1168
	v_add_f32_e32 v0, v0, v2
	v_div_scale_f32 v2, s[8:9], v0, v0, 1.0
	v_rcp_f32_e32 v3, v2
	v_div_scale_f32 v4, vcc, 1.0, v0, 1.0
	v_fma_f32 v5, -v2, v3, 1.0
	v_fmac_f32_e32 v3, v5, v3
	v_mul_f32_e32 v5, v4, v3
	v_fma_f32 v6, -v2, v5, v4
	v_fmac_f32_e32 v5, v6, v3
	v_fma_f32 v2, -v2, v5, v4
	v_div_fmas_f32 v2, v2, v3, v5
	v_div_fixup_f32 v0, v2, v0, 1.0
	v_pk_mul_f32 v[4:5], v[54:55], v[0:1] op_sel_hi:[1,0]
	v_pk_mul_f32 v[6:7], v[56:57], v[0:1] op_sel_hi:[1,0]
	v_lshl_add_u64 v[2:3], v[94:95], 0, v[98:99]
	v_cvt_pk_bf16_f32 v4, v4, v5
	v_cvt_pk_bf16_f32 v5, v6, v7
	flat_store_dwordx2 v[2:3], v[4:5]
	v_pk_mul_f32 v[4:5], v[50:51], v[0:1] op_sel_hi:[1,0]
	v_pk_mul_f32 v[6:7], v[52:53], v[0:1] op_sel_hi:[1,0]
	v_cvt_pk_bf16_f32 v4, v4, v5
	v_cvt_pk_bf16_f32 v5, v6, v7
	flat_store_dwordx2 v[2:3], v[4:5] offset:32
	v_pk_mul_f32 v[4:5], v[58:59], v[0:1] op_sel_hi:[1,0]
	v_pk_mul_f32 v[6:7], v[60:61], v[0:1] op_sel_hi:[1,0]
	v_cvt_pk_bf16_f32 v4, v4, v5
	v_cvt_pk_bf16_f32 v5, v6, v7
	flat_store_dwordx2 v[2:3], v[4:5] offset:64
	v_pk_mul_f32 v[4:5], v[62:63], v[0:1] op_sel_hi:[1,0]
	v_pk_mul_f32 v[6:7], v[64:65], v[0:1] op_sel_hi:[1,0]
	v_cvt_pk_bf16_f32 v4, v4, v5
	v_cvt_pk_bf16_f32 v5, v6, v7
	flat_store_dwordx2 v[2:3], v[4:5] offset:96
	v_pk_mul_f32 v[4:5], v[66:67], v[0:1] op_sel_hi:[1,0]
	v_pk_mul_f32 v[6:7], v[68:69], v[0:1] op_sel_hi:[1,0]
	v_cvt_pk_bf16_f32 v4, v4, v5
	v_cvt_pk_bf16_f32 v5, v6, v7
	flat_store_dwordx2 v[2:3], v[4:5] offset:128
	v_pk_mul_f32 v[4:5], v[70:71], v[0:1] op_sel_hi:[1,0]
	v_pk_mul_f32 v[6:7], v[72:73], v[0:1] op_sel_hi:[1,0]
	v_cvt_pk_bf16_f32 v4, v4, v5
	v_cvt_pk_bf16_f32 v5, v6, v7
	flat_store_dwordx2 v[2:3], v[4:5] offset:160
	v_pk_mul_f32 v[4:5], v[74:75], v[0:1] op_sel_hi:[1,0]
	v_pk_mul_f32 v[6:7], v[76:77], v[0:1] op_sel_hi:[1,0]
	v_cvt_pk_bf16_f32 v4, v4, v5
	v_cvt_pk_bf16_f32 v5, v6, v7
	flat_store_dwordx2 v[2:3], v[4:5] offset:192
	v_pk_mul_f32 v[4:5], v[78:79], v[0:1] op_sel_hi:[1,0]
	v_pk_mul_f32 v[6:7], v[80:81], v[0:1] op_sel_hi:[1,0]
	v_cvt_pk_bf16_f32 v4, v4, v5
	v_cvt_pk_bf16_f32 v5, v6, v7
	flat_store_dwordx2 v[2:3], v[4:5] offset:224
	s_branch .LBB0_1168

; DI void dsa_sparse_phase(unsigned char* lds, KParamPtr P, int wv) {
;     ...
;   const bool dealt = (gridDim.x == 256);
;   const int g_lo = dealt ? (int)kSpStart[blockIdx.x >> 3] : 0, g_n = dealt ? (int)kSpStart[(blockIdx.x >> 3) + 1] - g_lo : 0;
_ZL8kSpStart:
	.short	0
	.short	68
	.short	131
	.short	188
	.short	239
	.short	284
	.short	323
	.short	358
	.short	387
	.short	410
	.short	429
	.short	442
	.short	449
	.short	455
	.short	459
	.short	463
	.short	467
	.short	471
	.short	475
	.short	479
	.short	483
	.short	487
	.short	490
	.short	493
	.short	496
	.short	499
	.short	501
	.short	503
	.short	505
	.short	507
	.short	509
	.short	511
	.short	512
	.size	_ZL8kSpStart, 66

; __global__ void __launch_bounds__(NTHREADS) mega(Params P0) {
	.type	__hip_cuid_1ffeae86b4d56f0d,@object
